# baseline (speedup 1.0000x reference)
; #define LAS __attribute__((address_space(3)))
; #define GAS __attribute__((address_space(1)))
; __device__ __forceinline__ void attn_unit(LAS unsigned char* lds, bf16_t* Qm, const bf16_t* __restrict__ Kb, const bf16_t* __restrict__ Vt,
;                                           int b, int h, int qb, int lgS, float lam, float oscale, const float* __restrict__ subg, float* stash) {
;     ...
;             if (t + 3 < NT) *(LAS u32x4*)(lds + kq0 + kw) = kreg;
;             if (t + 2 < NT) { *(LAS u32x4*)(lds + vs2 + vw0) = vreg0; *(LAS u32x4*)(lds + vs2 + vw1) = vreg1; }
;             if (t + 4 < NT) kreg = *(const GAS u32x4*)(kg + (size_t)(t + 4) * 64 * 512);
;             if (t + 3 < NT) { vreg0 = *(const GAS u32x4*)(vg0 + (t + 3) * 64); vreg1 = *(const GAS u32x4*)(vg1 + (t + 3) * 64); }
.LBB0_335:
	s_mov_b32 s61, s50
	s_mov_b32 s50, s29
	s_mov_b32 s65, s28
	v_mfma_f32_32x32x16_bf16 v[96:111], v[156:159], v[136:139], v[64:79]
	v_mfma_f32_32x32x16_bf16 v[80:95], v[160:163], v[136:139], v[64:79]
	s_add_i32 s29, s57, 3
	s_cmp_lt_u32 s29, s38
	s_cselect_b64 s[30:31], -1, 0
	s_cmp_ge_u32 s29, s38
	s_cbranch_scc1 .Lmy_skip_kw
	v_add_u32_e32 v156, s60, v248
	s_waitcnt vmcnt(2)
	ds_write_b128 v156, v[152:155]
